# static s_setprio 1 for waves 4-7 around the stream K-loop (no per-segment flips)
# speedup vs baseline: 1.0096x; 1.0017x over previous
.LBB0_811:
	s_xor_b64 s[6:7], s[0:1], -1
	v_writelane_b32 v255, s6, 38
	s_cmp_lt_i32 s47, 1
	s_nop 0
	v_writelane_b32 v255, s7, 39
	s_cbranch_scc1 .LBB0_856
	v_readlane_b32 s6, v255, 21
	v_readlane_b32 s7, v255, 22
	s_nop 3
	s_and_b64 vcc, exec, s[6:7]
	s_cbranch_vccnz .Lprio_skip
	s_setprio 1
.Lprio_skip:
	s_abs_i32 s56, s33
	v_cvt_f32_u32_e32 v2, s56
	s_sub_i32 s12, 0, s56
	s_mov_b32 s89, s41
	s_ashr_i32 s97, s96, 31
	v_rcp_iflag_f32_e32 v2, v2
	s_ashr_i32 s95, s94, 31
	s_lshl_b64 s[6:7], s[88:89], 7
	s_lshl_b32 s14, s75, 6
	v_mul_f32_e32 v2, 0x4f7ffffe, v2
	v_cvt_u32_f32_e32 v2, v2
	s_lshl_b32 s48, s4, 8
	s_lshl_b32 s49, s3, 8
	s_lshl_b32 s15, s2, 6
	v_readfirstlane_b32 s13, v2
	s_mul_i32 s12, s12, s13
	s_mul_hi_u32 s12, s13, s12
	s_lshl_b64 s[8:9], s[96:97], 8
	s_lshl_b64 s[10:11], s[94:95], 8
	s_ashr_i32 s57, s33, 31
	s_add_i32 s58, s13, s12
	s_add_u32 s12, s6, 0x80
	v_mov_b32_e32 v197, v3
	v_mov_b32_e32 v201, v3
	s_addc_u32 s13, s7, 0
	s_add_i32 s59, s14, 0
	s_add_i32 s62, s15, 0
	s_waitcnt lgkmcnt(0)
	v_lshl_add_u64 v[4:5], s[12:13], 0, v[200:201]
	s_waitcnt vmcnt(0)
	v_lshl_add_u64 v[134:135], s[12:13], 0, v[196:197]
	s_mov_b64 s[50:51], 0
	s_mov_b32 s63, 2
	s_mov_b64 s[12:13], 0x100
	s_add_i32 s59, s59, 0x21400
	s_add_i32 s62, s62, 0x21400

.LBB0_857:
	s_setprio 0
	v_readlane_b32 s0, v255, 21
	v_readlane_b32 s1, v255, 22
	s_xor_b64 s[48:49], s[50:51], -1
	s_and_b64 vcc, exec, s[0:1]
	s_cbranch_vccz .LBB0_859
	s_barrier
